# nob3 + pool tile loop unrolled (gates up front)
# speedup vs baseline: 1.0813x; 1.0075x over previous
.LBB0_557:
	v_mov_b64_e32 v[34:35], s[28:29]
	v_lshl_or_b32 v104, s8, 8, v140
	v_mad_i64_i32 v[34:35], s[10:11], v32, s18, v[34:35]
	v_ashrrev_i32_e32 v105, 31, v104
	v_lshl_add_u64 v[106:107], v[34:35], 0, s[4:5]
	v_lshlrev_b64 v[34:35], 1, v[104:105]
	v_or_b32_e32 v108, 16, v104
	v_lshl_add_u64 v[36:37], v[106:107], 0, v[34:35]
	v_ashrrev_i32_e32 v109, 31, v108
	v_or_b32_e32 v110, 32, v104
	v_or_b32_e32 v112, 48, v104
	s_waitcnt lgkmcnt(0)
	s_barrier
	v_mov_b32_e32 v170, v36
	v_mov_b32_e32 v171, v37
	v_lshlrev_b64 v[132:133], 12, v[32:33]
	v_lshl_add_u64 v[130:131], v[104:105], 2, s[60:61]
	v_lshl_add_u64 v[132:133], s[30:31], 0, v[132:133]
	v_mov_b32_e32 v64, v143
	v_add_u32_e32 v103, 0x10800, v143
	v_lshl_add_u64 v[132:133], v[104:105], 1, v[132:133]
	ds_read_b128 v[174:177], v64
	ds_read_b128 v[178:181], v64 offset:64
	ds_read_b128 v[182:185], v64 offset:128
	ds_read_b128 v[186:189], v64 offset:192
	ds_read_b128 v[190:193], v64 offset:256
	ds_read_b128 v[194:197], v64 offset:320
	ds_read_b128 v[198:201], v64 offset:384
	ds_read_b128 v[202:205], v64 offset:448
	global_load_dwordx2 v[32:33], v[170:171], off
	global_load_dwordx2 v[34:35], v[170:171], off offset:32
	global_load_dwordx2 v[36:37], v[170:171], off offset:64
	global_load_dwordx2 v[38:39], v[170:171], off offset:96
	global_load_dwordx2 v[40:41], v[170:171], off offset:128
	global_load_dwordx2 v[42:43], v[170:171], off offset:160
	global_load_dwordx2 v[44:45], v[170:171], off offset:192
	global_load_dwordx2 v[46:47], v[170:171], off offset:224
	global_load_dwordx2 v[48:49], v[170:171], off offset:256
	global_load_dwordx2 v[50:51], v[170:171], off offset:288
	global_load_dwordx2 v[52:53], v[170:171], off offset:320
	global_load_dwordx2 v[54:55], v[170:171], off offset:352
	global_load_dwordx2 v[56:57], v[170:171], off offset:384
	global_load_dwordx2 v[58:59], v[170:171], off offset:416
	global_load_dwordx2 v[60:61], v[170:171], off offset:448
	global_load_dwordx2 v[62:63], v[170:171], off offset:480
	global_load_dwordx4 v[118:121], v[130:131], off
	global_load_dwordx4 v[122:125], v[130:131], off offset:64
	global_load_dwordx4 v[126:129], v[130:131], off offset:128
	s_waitcnt lgkmcnt(0)
	ds_read_b128 v[206:209], v64 offset:8448
	ds_read_b128 v[210:213], v64 offset:8512
	ds_read_b128 v[214:217], v64 offset:8576
	ds_read_b128 v[218:221], v64 offset:8640
	ds_read_b128 v[222:225], v64 offset:8704
	ds_read_b128 v[226:229], v64 offset:8768
	ds_read_b128 v[230:233], v64 offset:8832
	ds_read_b128 v[234:237], v64 offset:8896
	s_waitcnt vmcnt(26)
	v_mfma_f32_16x16x32_bf16 v[162:165], v[174:177], v[0:3], 0
	s_waitcnt vmcnt(25)
	v_mfma_f32_16x16x32_bf16 v[162:165], v[178:181], v[4:7], v[162:165]
	s_waitcnt vmcnt(24)
	v_mfma_f32_16x16x32_bf16 v[162:165], v[182:185], v[8:11], v[162:165]
	s_waitcnt vmcnt(23)
	v_mfma_f32_16x16x32_bf16 v[162:165], v[186:189], v[12:15], v[162:165]
	s_waitcnt vmcnt(22)
	v_mfma_f32_16x16x32_bf16 v[162:165], v[190:193], v[16:19], v[162:165]
	s_waitcnt vmcnt(21)
	v_mfma_f32_16x16x32_bf16 v[162:165], v[194:197], v[20:23], v[162:165]
	s_waitcnt vmcnt(20)
	v_mfma_f32_16x16x32_bf16 v[162:165], v[198:201], v[24:27], v[162:165]
	s_waitcnt vmcnt(19)
	v_mfma_f32_16x16x32_bf16 v[162:165], v[202:205], v[28:31], v[162:165]
	s_waitcnt vmcnt(18)
	v_lshlrev_b32_e32 v170, 16, v32
	v_and_b32_e32 v171, 0xffff0000, v32
	v_mul_f32_e32 v166, 0xbfb8aa3b, v170
	v_exp_f32_e32 v166, v166
	s_nop 0
	v_add_f32_e32 v166, 1.0, v166
	v_rcp_f32_e32 v172, v166
	v_mul_f32_e32 v166, 0xbfb8aa3b, v171
	v_exp_f32_e32 v166, v166
	s_nop 0
	v_add_f32_e32 v166, 1.0, v166
	v_rcp_f32_e32 v173, v166
	s_waitcnt vmcnt(2)
	v_pk_mul_f32 v[118:119], v[118:119], v[162:163]
	v_pk_mul_f32 v[120:121], v[120:121], v[164:165]
	v_pk_mul_f32 v[172:173], v[172:173], v[170:171]
	s_nop 0
	v_pk_mul_f32 v[118:119], v[172:173], v[118:119]
	s_nop 0
	v_cvt_pk_bf16_f32 v166, v118, v119
	v_lshlrev_b32_e32 v170, 16, v33
	v_and_b32_e32 v171, 0xffff0000, v33
	v_mul_f32_e32 v167, 0xbfb8aa3b, v170
	v_exp_f32_e32 v167, v167
	s_nop 0
	v_add_f32_e32 v167, 1.0, v167
	v_rcp_f32_e32 v172, v167
	v_mul_f32_e32 v167, 0xbfb8aa3b, v171
	v_exp_f32_e32 v167, v167
	s_nop 0
	v_add_f32_e32 v167, 1.0, v167
	v_rcp_f32_e32 v173, v167
	s_nop 1
	v_pk_mul_f32 v[172:173], v[172:173], v[170:171]
	s_nop 0
	v_pk_mul_f32 v[120:121], v[172:173], v[120:121]
	s_nop 0
	v_cvt_pk_bf16_f32 v167, v120, v121
	s_nop 0
	global_store_dwordx2 v[132:133], v[166:167], off offset:2048
	global_load_dwordx4 v[118:121], v[130:131], off offset:192
	s_waitcnt lgkmcnt(0)
	ds_read_b128 v[174:177], v64 offset:16896
	ds_read_b128 v[178:181], v64 offset:16960
	ds_read_b128 v[182:185], v64 offset:17024
	ds_read_b128 v[186:189], v64 offset:17088
	ds_read_b128 v[190:193], v64 offset:17152
	ds_read_b128 v[194:197], v64 offset:17216
	ds_read_b128 v[198:201], v64 offset:17280
	ds_read_b128 v[202:205], v64 offset:17344
	v_mfma_f32_16x16x32_bf16 v[162:165], v[206:209], v[0:3], 0
	v_mfma_f32_16x16x32_bf16 v[162:165], v[210:213], v[4:7], v[162:165]
	v_mfma_f32_16x16x32_bf16 v[162:165], v[214:217], v[8:11], v[162:165]
	v_mfma_f32_16x16x32_bf16 v[162:165], v[218:221], v[12:15], v[162:165]
	v_mfma_f32_16x16x32_bf16 v[162:165], v[222:225], v[16:19], v[162:165]
	v_mfma_f32_16x16x32_bf16 v[162:165], v[226:229], v[20:23], v[162:165]
	v_mfma_f32_16x16x32_bf16 v[162:165], v[230:233], v[24:27], v[162:165]
	v_mfma_f32_16x16x32_bf16 v[162:165], v[234:237], v[28:31], v[162:165]
	s_waitcnt vmcnt(19)
	v_lshlrev_b32_e32 v170, 16, v34
	v_and_b32_e32 v171, 0xffff0000, v34
	v_mul_f32_e32 v166, 0xbfb8aa3b, v170
	v_exp_f32_e32 v166, v166
	s_nop 0
	v_add_f32_e32 v166, 1.0, v166
	v_rcp_f32_e32 v172, v166
	v_mul_f32_e32 v166, 0xbfb8aa3b, v171
	v_exp_f32_e32 v166, v166
	s_nop 0
	v_add_f32_e32 v166, 1.0, v166
	v_rcp_f32_e32 v173, v166
	s_waitcnt vmcnt(3)
	v_pk_mul_f32 v[122:123], v[122:123], v[162:163]
	v_pk_mul_f32 v[124:125], v[124:125], v[164:165]
	v_pk_mul_f32 v[172:173], v[172:173], v[170:171]
	s_nop 0
	v_pk_mul_f32 v[122:123], v[172:173], v[122:123]
	s_nop 0
	v_cvt_pk_bf16_f32 v166, v122, v123
	v_lshlrev_b32_e32 v170, 16, v35
	v_and_b32_e32 v171, 0xffff0000, v35
	v_mul_f32_e32 v167, 0xbfb8aa3b, v170
	v_exp_f32_e32 v167, v167
	s_nop 0
	v_add_f32_e32 v167, 1.0, v167
	v_rcp_f32_e32 v172, v167
	v_mul_f32_e32 v167, 0xbfb8aa3b, v171
	v_exp_f32_e32 v167, v167
	s_nop 0
	v_add_f32_e32 v167, 1.0, v167
	v_rcp_f32_e32 v173, v167
	s_nop 1
	v_pk_mul_f32 v[172:173], v[172:173], v[170:171]
	s_nop 0
	v_pk_mul_f32 v[124:125], v[172:173], v[124:125]
	s_nop 0
	v_cvt_pk_bf16_f32 v167, v124, v125
	s_nop 0
	global_store_dwordx2 v[132:133], v[166:167], off offset:2080
	global_load_dwordx4 v[122:125], v[130:131], off offset:256
	s_waitcnt lgkmcnt(0)
	ds_read_b128 v[206:209], v64 offset:25344
	ds_read_b128 v[210:213], v64 offset:25408
	ds_read_b128 v[214:217], v64 offset:25472
	ds_read_b128 v[218:221], v64 offset:25536
	ds_read_b128 v[222:225], v64 offset:25600
	ds_read_b128 v[226:229], v64 offset:25664
	ds_read_b128 v[230:233], v64 offset:25728
	ds_read_b128 v[234:237], v64 offset:25792
	v_mfma_f32_16x16x32_bf16 v[162:165], v[174:177], v[0:3], 0
	v_mfma_f32_16x16x32_bf16 v[162:165], v[178:181], v[4:7], v[162:165]
	v_mfma_f32_16x16x32_bf16 v[162:165], v[182:185], v[8:11], v[162:165]
	v_mfma_f32_16x16x32_bf16 v[162:165], v[186:189], v[12:15], v[162:165]
	v_mfma_f32_16x16x32_bf16 v[162:165], v[190:193], v[16:19], v[162:165]
	v_mfma_f32_16x16x32_bf16 v[162:165], v[194:197], v[20:23], v[162:165]
	v_mfma_f32_16x16x32_bf16 v[162:165], v[198:201], v[24:27], v[162:165]
	v_mfma_f32_16x16x32_bf16 v[162:165], v[202:205], v[28:31], v[162:165]
	s_waitcnt vmcnt(20)
	v_lshlrev_b32_e32 v170, 16, v36
	v_and_b32_e32 v171, 0xffff0000, v36
	v_mul_f32_e32 v166, 0xbfb8aa3b, v170
	v_exp_f32_e32 v166, v166
	s_nop 0
	v_add_f32_e32 v166, 1.0, v166
	v_rcp_f32_e32 v172, v166
	v_mul_f32_e32 v166, 0xbfb8aa3b, v171
	v_exp_f32_e32 v166, v166
	s_nop 0
	v_add_f32_e32 v166, 1.0, v166
	v_rcp_f32_e32 v173, v166
	s_waitcnt vmcnt(4)
	v_pk_mul_f32 v[126:127], v[126:127], v[162:163]
	v_pk_mul_f32 v[128:129], v[128:129], v[164:165]
	v_pk_mul_f32 v[172:173], v[172:173], v[170:171]
	s_nop 0
	v_pk_mul_f32 v[126:127], v[172:173], v[126:127]
	s_nop 0
	v_cvt_pk_bf16_f32 v166, v126, v127
	v_lshlrev_b32_e32 v170, 16, v37
	v_and_b32_e32 v171, 0xffff0000, v37
	v_mul_f32_e32 v167, 0xbfb8aa3b, v170
	v_exp_f32_e32 v167, v167
	s_nop 0
	v_add_f32_e32 v167, 1.0, v167
	v_rcp_f32_e32 v172, v167
	v_mul_f32_e32 v167, 0xbfb8aa3b, v171
	v_exp_f32_e32 v167, v167
	s_nop 0
	v_add_f32_e32 v167, 1.0, v167
	v_rcp_f32_e32 v173, v167
	s_nop 1
	v_pk_mul_f32 v[172:173], v[172:173], v[170:171]
	s_nop 0
	v_pk_mul_f32 v[128:129], v[172:173], v[128:129]
	s_nop 0
	v_cvt_pk_bf16_f32 v167, v128, v129
	s_nop 0
	global_store_dwordx2 v[132:133], v[166:167], off offset:2112
	global_load_dwordx4 v[126:129], v[130:131], off offset:320
	s_waitcnt lgkmcnt(0)
	ds_read_b128 v[174:177], v64 offset:33792
	ds_read_b128 v[178:181], v64 offset:33856
	ds_read_b128 v[182:185], v64 offset:33920
	ds_read_b128 v[186:189], v64 offset:33984
	ds_read_b128 v[190:193], v64 offset:34048
	ds_read_b128 v[194:197], v64 offset:34112
	ds_read_b128 v[198:201], v64 offset:34176
	ds_read_b128 v[202:205], v64 offset:34240
	v_mfma_f32_16x16x32_bf16 v[162:165], v[206:209], v[0:3], 0
	v_mfma_f32_16x16x32_bf16 v[162:165], v[210:213], v[4:7], v[162:165]
	v_mfma_f32_16x16x32_bf16 v[162:165], v[214:217], v[8:11], v[162:165]
	v_mfma_f32_16x16x32_bf16 v[162:165], v[218:221], v[12:15], v[162:165]
	v_mfma_f32_16x16x32_bf16 v[162:165], v[222:225], v[16:19], v[162:165]
	v_mfma_f32_16x16x32_bf16 v[162:165], v[226:229], v[20:23], v[162:165]
	v_mfma_f32_16x16x32_bf16 v[162:165], v[230:233], v[24:27], v[162:165]
	v_mfma_f32_16x16x32_bf16 v[162:165], v[234:237], v[28:31], v[162:165]
	s_waitcnt vmcnt(21)
	v_lshlrev_b32_e32 v170, 16, v38
	v_and_b32_e32 v171, 0xffff0000, v38
	v_mul_f32_e32 v166, 0xbfb8aa3b, v170
	v_exp_f32_e32 v166, v166
	s_nop 0
	v_add_f32_e32 v166, 1.0, v166
	v_rcp_f32_e32 v172, v166
	v_mul_f32_e32 v166, 0xbfb8aa3b, v171
	v_exp_f32_e32 v166, v166
	s_nop 0
	v_add_f32_e32 v166, 1.0, v166
	v_rcp_f32_e32 v173, v166
	s_waitcnt vmcnt(4)
	v_pk_mul_f32 v[118:119], v[118:119], v[162:163]
	v_pk_mul_f32 v[120:121], v[120:121], v[164:165]
	v_pk_mul_f32 v[172:173], v[172:173], v[170:171]
	s_nop 0
	v_pk_mul_f32 v[118:119], v[172:173], v[118:119]
	s_nop 0
	v_cvt_pk_bf16_f32 v166, v118, v119
	v_lshlrev_b32_e32 v170, 16, v39
	v_and_b32_e32 v171, 0xffff0000, v39
	v_mul_f32_e32 v167, 0xbfb8aa3b, v170
	v_exp_f32_e32 v167, v167
	s_nop 0
	v_add_f32_e32 v167, 1.0, v167
	v_rcp_f32_e32 v172, v167
	v_mul_f32_e32 v167, 0xbfb8aa3b, v171
	v_exp_f32_e32 v167, v167
	s_nop 0
	v_add_f32_e32 v167, 1.0, v167
	v_rcp_f32_e32 v173, v167
	s_nop 1
	v_pk_mul_f32 v[172:173], v[172:173], v[170:171]
	s_nop 0
	v_pk_mul_f32 v[120:121], v[172:173], v[120:121]
	s_nop 0
	v_cvt_pk_bf16_f32 v167, v120, v121
	s_nop 0
	global_store_dwordx2 v[132:133], v[166:167], off offset:2144
	global_load_dwordx4 v[118:121], v[130:131], off offset:384
	s_waitcnt lgkmcnt(0)
	ds_read_b128 v[206:209], v64 offset:42240
	ds_read_b128 v[210:213], v64 offset:42304
	ds_read_b128 v[214:217], v64 offset:42368
	ds_read_b128 v[218:221], v64 offset:42432
	ds_read_b128 v[222:225], v64 offset:42496
	ds_read_b128 v[226:229], v64 offset:42560
	ds_read_b128 v[230:233], v64 offset:42624
	ds_read_b128 v[234:237], v64 offset:42688
	v_mfma_f32_16x16x32_bf16 v[162:165], v[174:177], v[0:3], 0
	v_mfma_f32_16x16x32_bf16 v[162:165], v[178:181], v[4:7], v[162:165]
	v_mfma_f32_16x16x32_bf16 v[162:165], v[182:185], v[8:11], v[162:165]
	v_mfma_f32_16x16x32_bf16 v[162:165], v[186:189], v[12:15], v[162:165]
	v_mfma_f32_16x16x32_bf16 v[162:165], v[190:193], v[16:19], v[162:165]
	v_mfma_f32_16x16x32_bf16 v[162:165], v[194:197], v[20:23], v[162:165]
	v_mfma_f32_16x16x32_bf16 v[162:165], v[198:201], v[24:27], v[162:165]
	v_mfma_f32_16x16x32_bf16 v[162:165], v[202:205], v[28:31], v[162:165]
	s_waitcnt vmcnt(22)
	v_lshlrev_b32_e32 v170, 16, v40
	v_and_b32_e32 v171, 0xffff0000, v40
	v_mul_f32_e32 v166, 0xbfb8aa3b, v170
	v_exp_f32_e32 v166, v166
	s_nop 0
	v_add_f32_e32 v166, 1.0, v166
	v_rcp_f32_e32 v172, v166
	v_mul_f32_e32 v166, 0xbfb8aa3b, v171
	v_exp_f32_e32 v166, v166
	s_nop 0
	v_add_f32_e32 v166, 1.0, v166
	v_rcp_f32_e32 v173, v166
	s_waitcnt vmcnt(4)
	v_pk_mul_f32 v[122:123], v[122:123], v[162:163]
	v_pk_mul_f32 v[124:125], v[124:125], v[164:165]
	v_pk_mul_f32 v[172:173], v[172:173], v[170:171]
	s_nop 0
	v_pk_mul_f32 v[122:123], v[172:173], v[122:123]
	s_nop 0
	v_cvt_pk_bf16_f32 v166, v122, v123
	v_lshlrev_b32_e32 v170, 16, v41
	v_and_b32_e32 v171, 0xffff0000, v41
	v_mul_f32_e32 v167, 0xbfb8aa3b, v170
	v_exp_f32_e32 v167, v167
	s_nop 0
	v_add_f32_e32 v167, 1.0, v167
	v_rcp_f32_e32 v172, v167
	v_mul_f32_e32 v167, 0xbfb8aa3b, v171
	v_exp_f32_e32 v167, v167
	s_nop 0
	v_add_f32_e32 v167, 1.0, v167
	v_rcp_f32_e32 v173, v167
	s_nop 1
	v_pk_mul_f32 v[172:173], v[172:173], v[170:171]
	s_nop 0
	v_pk_mul_f32 v[124:125], v[172:173], v[124:125]
	s_nop 0
	v_cvt_pk_bf16_f32 v167, v124, v125
	s_nop 0
	global_store_dwordx2 v[132:133], v[166:167], off offset:2176
	global_load_dwordx4 v[122:125], v[130:131], off offset:448
	s_waitcnt lgkmcnt(0)
	ds_read_b128 v[174:177], v64 offset:50688
	ds_read_b128 v[178:181], v64 offset:50752
	ds_read_b128 v[182:185], v64 offset:50816
	ds_read_b128 v[186:189], v64 offset:50880
	ds_read_b128 v[190:193], v64 offset:50944
	ds_read_b128 v[194:197], v64 offset:51008
	ds_read_b128 v[198:201], v64 offset:51072
	ds_read_b128 v[202:205], v64 offset:51136
	v_mfma_f32_16x16x32_bf16 v[162:165], v[206:209], v[0:3], 0
	v_mfma_f32_16x16x32_bf16 v[162:165], v[210:213], v[4:7], v[162:165]
	v_mfma_f32_16x16x32_bf16 v[162:165], v[214:217], v[8:11], v[162:165]
	v_mfma_f32_16x16x32_bf16 v[162:165], v[218:221], v[12:15], v[162:165]
	v_mfma_f32_16x16x32_bf16 v[162:165], v[222:225], v[16:19], v[162:165]
	v_mfma_f32_16x16x32_bf16 v[162:165], v[226:229], v[20:23], v[162:165]
	v_mfma_f32_16x16x32_bf16 v[162:165], v[230:233], v[24:27], v[162:165]
	v_mfma_f32_16x16x32_bf16 v[162:165], v[234:237], v[28:31], v[162:165]
	s_waitcnt vmcnt(23)
	v_lshlrev_b32_e32 v170, 16, v42
	v_and_b32_e32 v171, 0xffff0000, v42
	v_mul_f32_e32 v166, 0xbfb8aa3b, v170
	v_exp_f32_e32 v166, v166
	s_nop 0
	v_add_f32_e32 v166, 1.0, v166
	v_rcp_f32_e32 v172, v166
	v_mul_f32_e32 v166, 0xbfb8aa3b, v171
	v_exp_f32_e32 v166, v166
	s_nop 0
	v_add_f32_e32 v166, 1.0, v166
	v_rcp_f32_e32 v173, v166
	s_waitcnt vmcnt(4)
	v_pk_mul_f32 v[126:127], v[126:127], v[162:163]
	v_pk_mul_f32 v[128:129], v[128:129], v[164:165]
	v_pk_mul_f32 v[172:173], v[172:173], v[170:171]
	s_nop 0
	v_pk_mul_f32 v[126:127], v[172:173], v[126:127]
	s_nop 0
	v_cvt_pk_bf16_f32 v166, v126, v127
	v_lshlrev_b32_e32 v170, 16, v43
	v_and_b32_e32 v171, 0xffff0000, v43
	v_mul_f32_e32 v167, 0xbfb8aa3b, v170
	v_exp_f32_e32 v167, v167
	s_nop 0
	v_add_f32_e32 v167, 1.0, v167
	v_rcp_f32_e32 v172, v167
	v_mul_f32_e32 v167, 0xbfb8aa3b, v171
	v_exp_f32_e32 v167, v167
	s_nop 0
	v_add_f32_e32 v167, 1.0, v167
	v_rcp_f32_e32 v173, v167
	s_nop 1
	v_pk_mul_f32 v[172:173], v[172:173], v[170:171]
	s_nop 0
	v_pk_mul_f32 v[128:129], v[172:173], v[128:129]
	s_nop 0
	v_cvt_pk_bf16_f32 v167, v128, v129
	s_nop 0
	global_store_dwordx2 v[132:133], v[166:167], off offset:2208
	global_load_dwordx4 v[126:129], v[130:131], off offset:512
	s_waitcnt lgkmcnt(0)
	ds_read_b128 v[206:209], v64 offset:59136
	ds_read_b128 v[210:213], v64 offset:59200
	ds_read_b128 v[214:217], v64 offset:59264
	ds_read_b128 v[218:221], v64 offset:59328
	ds_read_b128 v[222:225], v64 offset:59392
	ds_read_b128 v[226:229], v64 offset:59456
	ds_read_b128 v[230:233], v64 offset:59520
	ds_read_b128 v[234:237], v64 offset:59584
	v_mfma_f32_16x16x32_bf16 v[162:165], v[174:177], v[0:3], 0
	v_mfma_f32_16x16x32_bf16 v[162:165], v[178:181], v[4:7], v[162:165]
	v_mfma_f32_16x16x32_bf16 v[162:165], v[182:185], v[8:11], v[162:165]
	v_mfma_f32_16x16x32_bf16 v[162:165], v[186:189], v[12:15], v[162:165]
	v_mfma_f32_16x16x32_bf16 v[162:165], v[190:193], v[16:19], v[162:165]
	v_mfma_f32_16x16x32_bf16 v[162:165], v[194:197], v[20:23], v[162:165]
	v_mfma_f32_16x16x32_bf16 v[162:165], v[198:201], v[24:27], v[162:165]
	v_mfma_f32_16x16x32_bf16 v[162:165], v[202:205], v[28:31], v[162:165]
	s_waitcnt vmcnt(24)
	v_lshlrev_b32_e32 v170, 16, v44
	v_and_b32_e32 v171, 0xffff0000, v44
	v_mul_f32_e32 v166, 0xbfb8aa3b, v170
	v_exp_f32_e32 v166, v166
	s_nop 0
	v_add_f32_e32 v166, 1.0, v166
	v_rcp_f32_e32 v172, v166
	v_mul_f32_e32 v166, 0xbfb8aa3b, v171
	v_exp_f32_e32 v166, v166
	s_nop 0
	v_add_f32_e32 v166, 1.0, v166
	v_rcp_f32_e32 v173, v166
	s_waitcnt vmcnt(4)
	v_pk_mul_f32 v[118:119], v[118:119], v[162:163]
	v_pk_mul_f32 v[120:121], v[120:121], v[164:165]
	v_pk_mul_f32 v[172:173], v[172:173], v[170:171]
	s_nop 0
	v_pk_mul_f32 v[118:119], v[172:173], v[118:119]
	s_nop 0
	v_cvt_pk_bf16_f32 v166, v118, v119
	v_lshlrev_b32_e32 v170, 16, v45
	v_and_b32_e32 v171, 0xffff0000, v45
	v_mul_f32_e32 v167, 0xbfb8aa3b, v170
	v_exp_f32_e32 v167, v167
	s_nop 0
	v_add_f32_e32 v167, 1.0, v167
	v_rcp_f32_e32 v172, v167
	v_mul_f32_e32 v167, 0xbfb8aa3b, v171
	v_exp_f32_e32 v167, v167
	s_nop 0
	v_add_f32_e32 v167, 1.0, v167
	v_rcp_f32_e32 v173, v167
	s_nop 1
	v_pk_mul_f32 v[172:173], v[172:173], v[170:171]
	s_nop 0
	v_pk_mul_f32 v[120:121], v[172:173], v[120:121]
	s_nop 0
	v_cvt_pk_bf16_f32 v167, v120, v121
	s_nop 0
	global_store_dwordx2 v[132:133], v[166:167], off offset:2240
	global_load_dwordx4 v[118:121], v[130:131], off offset:576
	s_waitcnt lgkmcnt(0)
	ds_read_b128 v[174:177], v103
	ds_read_b128 v[178:181], v103 offset:64
	ds_read_b128 v[182:185], v103 offset:128
	ds_read_b128 v[186:189], v103 offset:192
	ds_read_b128 v[190:193], v103 offset:256
	ds_read_b128 v[194:197], v103 offset:320
	ds_read_b128 v[198:201], v103 offset:384
	ds_read_b128 v[202:205], v103 offset:448
	v_mfma_f32_16x16x32_bf16 v[162:165], v[206:209], v[0:3], 0
	v_mfma_f32_16x16x32_bf16 v[162:165], v[210:213], v[4:7], v[162:165]
	v_mfma_f32_16x16x32_bf16 v[162:165], v[214:217], v[8:11], v[162:165]
	v_mfma_f32_16x16x32_bf16 v[162:165], v[218:221], v[12:15], v[162:165]
	v_mfma_f32_16x16x32_bf16 v[162:165], v[222:225], v[16:19], v[162:165]
	v_mfma_f32_16x16x32_bf16 v[162:165], v[226:229], v[20:23], v[162:165]
	v_mfma_f32_16x16x32_bf16 v[162:165], v[230:233], v[24:27], v[162:165]
	v_mfma_f32_16x16x32_bf16 v[162:165], v[234:237], v[28:31], v[162:165]
	s_waitcnt vmcnt(25)
	v_lshlrev_b32_e32 v170, 16, v46
	v_and_b32_e32 v171, 0xffff0000, v46
	v_mul_f32_e32 v166, 0xbfb8aa3b, v170
	v_exp_f32_e32 v166, v166
	s_nop 0
	v_add_f32_e32 v166, 1.0, v166
	v_rcp_f32_e32 v172, v166
	v_mul_f32_e32 v166, 0xbfb8aa3b, v171
	v_exp_f32_e32 v166, v166
	s_nop 0
	v_add_f32_e32 v166, 1.0, v166
	v_rcp_f32_e32 v173, v166
	s_waitcnt vmcnt(4)
	v_pk_mul_f32 v[122:123], v[122:123], v[162:163]
	v_pk_mul_f32 v[124:125], v[124:125], v[164:165]
	v_pk_mul_f32 v[172:173], v[172:173], v[170:171]
	s_nop 0
	v_pk_mul_f32 v[122:123], v[172:173], v[122:123]
	s_nop 0
	v_cvt_pk_bf16_f32 v166, v122, v123
	v_lshlrev_b32_e32 v170, 16, v47
	v_and_b32_e32 v171, 0xffff0000, v47
	v_mul_f32_e32 v167, 0xbfb8aa3b, v170
	v_exp_f32_e32 v167, v167
	s_nop 0
	v_add_f32_e32 v167, 1.0, v167
	v_rcp_f32_e32 v172, v167
	v_mul_f32_e32 v167, 0xbfb8aa3b, v171
	v_exp_f32_e32 v167, v167
	s_nop 0
	v_add_f32_e32 v167, 1.0, v167
	v_rcp_f32_e32 v173, v167
	s_nop 1
	v_pk_mul_f32 v[172:173], v[172:173], v[170:171]
	s_nop 0
	v_pk_mul_f32 v[124:125], v[172:173], v[124:125]
	s_nop 0
	v_cvt_pk_bf16_f32 v167, v124, v125
	s_nop 0
	global_store_dwordx2 v[132:133], v[166:167], off offset:2272
	global_load_dwordx4 v[122:125], v[130:131], off offset:640
	s_waitcnt lgkmcnt(0)
	ds_read_b128 v[206:209], v103 offset:8448
	ds_read_b128 v[210:213], v103 offset:8512
	ds_read_b128 v[214:217], v103 offset:8576
	ds_read_b128 v[218:221], v103 offset:8640
	ds_read_b128 v[222:225], v103 offset:8704
	ds_read_b128 v[226:229], v103 offset:8768
	ds_read_b128 v[230:233], v103 offset:8832
	ds_read_b128 v[234:237], v103 offset:8896
	v_mfma_f32_16x16x32_bf16 v[162:165], v[174:177], v[0:3], 0
	v_mfma_f32_16x16x32_bf16 v[162:165], v[178:181], v[4:7], v[162:165]
	v_mfma_f32_16x16x32_bf16 v[162:165], v[182:185], v[8:11], v[162:165]
	v_mfma_f32_16x16x32_bf16 v[162:165], v[186:189], v[12:15], v[162:165]
	v_mfma_f32_16x16x32_bf16 v[162:165], v[190:193], v[16:19], v[162:165]
	v_mfma_f32_16x16x32_bf16 v[162:165], v[194:197], v[20:23], v[162:165]
	v_mfma_f32_16x16x32_bf16 v[162:165], v[198:201], v[24:27], v[162:165]
	v_mfma_f32_16x16x32_bf16 v[162:165], v[202:205], v[28:31], v[162:165]
	s_waitcnt vmcnt(26)
	v_lshlrev_b32_e32 v170, 16, v48
	v_and_b32_e32 v171, 0xffff0000, v48
	v_mul_f32_e32 v166, 0xbfb8aa3b, v170
	v_exp_f32_e32 v166, v166
	s_nop 0
	v_add_f32_e32 v166, 1.0, v166
	v_rcp_f32_e32 v172, v166
	v_mul_f32_e32 v166, 0xbfb8aa3b, v171
	v_exp_f32_e32 v166, v166
	s_nop 0
	v_add_f32_e32 v166, 1.0, v166
	v_rcp_f32_e32 v173, v166
	s_waitcnt vmcnt(4)
	v_pk_mul_f32 v[126:127], v[126:127], v[162:163]
	v_pk_mul_f32 v[128:129], v[128:129], v[164:165]
	v_pk_mul_f32 v[172:173], v[172:173], v[170:171]
	s_nop 0
	v_pk_mul_f32 v[126:127], v[172:173], v[126:127]
	s_nop 0
	v_cvt_pk_bf16_f32 v166, v126, v127
	v_lshlrev_b32_e32 v170, 16, v49
	v_and_b32_e32 v171, 0xffff0000, v49
	v_mul_f32_e32 v167, 0xbfb8aa3b, v170
	v_exp_f32_e32 v167, v167
	s_nop 0
	v_add_f32_e32 v167, 1.0, v167
	v_rcp_f32_e32 v172, v167
	v_mul_f32_e32 v167, 0xbfb8aa3b, v171
	v_exp_f32_e32 v167, v167
	s_nop 0
	v_add_f32_e32 v167, 1.0, v167
	v_rcp_f32_e32 v173, v167
	s_nop 1
	v_pk_mul_f32 v[172:173], v[172:173], v[170:171]
	s_nop 0
	v_pk_mul_f32 v[128:129], v[172:173], v[128:129]
	s_nop 0
	v_cvt_pk_bf16_f32 v167, v128, v129
	s_nop 0
	global_store_dwordx2 v[132:133], v[166:167], off offset:2304
	global_load_dwordx4 v[126:129], v[130:131], off offset:704
	s_waitcnt lgkmcnt(0)
	ds_read_b128 v[174:177], v103 offset:16896
	ds_read_b128 v[178:181], v103 offset:16960
	ds_read_b128 v[182:185], v103 offset:17024
	ds_read_b128 v[186:189], v103 offset:17088
	ds_read_b128 v[190:193], v103 offset:17152
	ds_read_b128 v[194:197], v103 offset:17216
	ds_read_b128 v[198:201], v103 offset:17280
	ds_read_b128 v[202:205], v103 offset:17344
	v_mfma_f32_16x16x32_bf16 v[162:165], v[206:209], v[0:3], 0
	v_mfma_f32_16x16x32_bf16 v[162:165], v[210:213], v[4:7], v[162:165]
	v_mfma_f32_16x16x32_bf16 v[162:165], v[214:217], v[8:11], v[162:165]
	v_mfma_f32_16x16x32_bf16 v[162:165], v[218:221], v[12:15], v[162:165]
	v_mfma_f32_16x16x32_bf16 v[162:165], v[222:225], v[16:19], v[162:165]
	v_mfma_f32_16x16x32_bf16 v[162:165], v[226:229], v[20:23], v[162:165]
	v_mfma_f32_16x16x32_bf16 v[162:165], v[230:233], v[24:27], v[162:165]
	v_mfma_f32_16x16x32_bf16 v[162:165], v[234:237], v[28:31], v[162:165]
	s_waitcnt vmcnt(27)
	v_lshlrev_b32_e32 v170, 16, v50
	v_and_b32_e32 v171, 0xffff0000, v50
	v_mul_f32_e32 v166, 0xbfb8aa3b, v170
	v_exp_f32_e32 v166, v166
	s_nop 0
	v_add_f32_e32 v166, 1.0, v166
	v_rcp_f32_e32 v172, v166
	v_mul_f32_e32 v166, 0xbfb8aa3b, v171
	v_exp_f32_e32 v166, v166
	s_nop 0
	v_add_f32_e32 v166, 1.0, v166
	v_rcp_f32_e32 v173, v166
	s_waitcnt vmcnt(4)
	v_pk_mul_f32 v[118:119], v[118:119], v[162:163]
	v_pk_mul_f32 v[120:121], v[120:121], v[164:165]
	v_pk_mul_f32 v[172:173], v[172:173], v[170:171]
	s_nop 0
	v_pk_mul_f32 v[118:119], v[172:173], v[118:119]
	s_nop 0
	v_cvt_pk_bf16_f32 v166, v118, v119
	v_lshlrev_b32_e32 v170, 16, v51
	v_and_b32_e32 v171, 0xffff0000, v51
	v_mul_f32_e32 v167, 0xbfb8aa3b, v170
	v_exp_f32_e32 v167, v167
	s_nop 0
	v_add_f32_e32 v167, 1.0, v167
	v_rcp_f32_e32 v172, v167
	v_mul_f32_e32 v167, 0xbfb8aa3b, v171
	v_exp_f32_e32 v167, v167
	s_nop 0
	v_add_f32_e32 v167, 1.0, v167
	v_rcp_f32_e32 v173, v167
	s_nop 1
	v_pk_mul_f32 v[172:173], v[172:173], v[170:171]
	s_nop 0
	v_pk_mul_f32 v[120:121], v[172:173], v[120:121]
	s_nop 0
	v_cvt_pk_bf16_f32 v167, v120, v121
	s_nop 0
	global_store_dwordx2 v[132:133], v[166:167], off offset:2336
	global_load_dwordx4 v[118:121], v[130:131], off offset:768
	s_waitcnt lgkmcnt(0)
	ds_read_b128 v[206:209], v103 offset:25344
	ds_read_b128 v[210:213], v103 offset:25408
	ds_read_b128 v[214:217], v103 offset:25472
	ds_read_b128 v[218:221], v103 offset:25536
	ds_read_b128 v[222:225], v103 offset:25600
	ds_read_b128 v[226:229], v103 offset:25664
	ds_read_b128 v[230:233], v103 offset:25728
	ds_read_b128 v[234:237], v103 offset:25792
	v_mfma_f32_16x16x32_bf16 v[162:165], v[174:177], v[0:3], 0
	v_mfma_f32_16x16x32_bf16 v[162:165], v[178:181], v[4:7], v[162:165]
	v_mfma_f32_16x16x32_bf16 v[162:165], v[182:185], v[8:11], v[162:165]
	v_mfma_f32_16x16x32_bf16 v[162:165], v[186:189], v[12:15], v[162:165]
	v_mfma_f32_16x16x32_bf16 v[162:165], v[190:193], v[16:19], v[162:165]
	v_mfma_f32_16x16x32_bf16 v[162:165], v[194:197], v[20:23], v[162:165]
	v_mfma_f32_16x16x32_bf16 v[162:165], v[198:201], v[24:27], v[162:165]
	v_mfma_f32_16x16x32_bf16 v[162:165], v[202:205], v[28:31], v[162:165]
	s_waitcnt vmcnt(28)
	v_lshlrev_b32_e32 v170, 16, v52
	v_and_b32_e32 v171, 0xffff0000, v52
	v_mul_f32_e32 v166, 0xbfb8aa3b, v170
	v_exp_f32_e32 v166, v166
	s_nop 0
	v_add_f32_e32 v166, 1.0, v166
	v_rcp_f32_e32 v172, v166
	v_mul_f32_e32 v166, 0xbfb8aa3b, v171
	v_exp_f32_e32 v166, v166
	s_nop 0
	v_add_f32_e32 v166, 1.0, v166
	v_rcp_f32_e32 v173, v166
	s_waitcnt vmcnt(4)
	v_pk_mul_f32 v[122:123], v[122:123], v[162:163]
	v_pk_mul_f32 v[124:125], v[124:125], v[164:165]
	v_pk_mul_f32 v[172:173], v[172:173], v[170:171]
	s_nop 0
	v_pk_mul_f32 v[122:123], v[172:173], v[122:123]
	s_nop 0
	v_cvt_pk_bf16_f32 v166, v122, v123
	v_lshlrev_b32_e32 v170, 16, v53
	v_and_b32_e32 v171, 0xffff0000, v53
	v_mul_f32_e32 v167, 0xbfb8aa3b, v170
	v_exp_f32_e32 v167, v167
	s_nop 0
	v_add_f32_e32 v167, 1.0, v167
	v_rcp_f32_e32 v172, v167
	v_mul_f32_e32 v167, 0xbfb8aa3b, v171
	v_exp_f32_e32 v167, v167
	s_nop 0
	v_add_f32_e32 v167, 1.0, v167
	v_rcp_f32_e32 v173, v167
	s_nop 1
	v_pk_mul_f32 v[172:173], v[172:173], v[170:171]
	s_nop 0
	v_pk_mul_f32 v[124:125], v[172:173], v[124:125]
	s_nop 0
	v_cvt_pk_bf16_f32 v167, v124, v125
	s_nop 0
	global_store_dwordx2 v[132:133], v[166:167], off offset:2368
	global_load_dwordx4 v[122:125], v[130:131], off offset:832
	s_waitcnt lgkmcnt(0)
	ds_read_b128 v[174:177], v103 offset:33792
	ds_read_b128 v[178:181], v103 offset:33856
	ds_read_b128 v[182:185], v103 offset:33920
	ds_read_b128 v[186:189], v103 offset:33984
	ds_read_b128 v[190:193], v103 offset:34048
	ds_read_b128 v[194:197], v103 offset:34112
	ds_read_b128 v[198:201], v103 offset:34176
	ds_read_b128 v[202:205], v103 offset:34240
	v_mfma_f32_16x16x32_bf16 v[162:165], v[206:209], v[0:3], 0
	v_mfma_f32_16x16x32_bf16 v[162:165], v[210:213], v[4:7], v[162:165]
	v_mfma_f32_16x16x32_bf16 v[162:165], v[214:217], v[8:11], v[162:165]
	v_mfma_f32_16x16x32_bf16 v[162:165], v[218:221], v[12:15], v[162:165]
	v_mfma_f32_16x16x32_bf16 v[162:165], v[222:225], v[16:19], v[162:165]
	v_mfma_f32_16x16x32_bf16 v[162:165], v[226:229], v[20:23], v[162:165]
	v_mfma_f32_16x16x32_bf16 v[162:165], v[230:233], v[24:27], v[162:165]
	v_mfma_f32_16x16x32_bf16 v[162:165], v[234:237], v[28:31], v[162:165]
	s_waitcnt vmcnt(29)
	v_lshlrev_b32_e32 v170, 16, v54
	v_and_b32_e32 v171, 0xffff0000, v54
	v_mul_f32_e32 v166, 0xbfb8aa3b, v170
	v_exp_f32_e32 v166, v166
	s_nop 0
	v_add_f32_e32 v166, 1.0, v166
	v_rcp_f32_e32 v172, v166
	v_mul_f32_e32 v166, 0xbfb8aa3b, v171
	v_exp_f32_e32 v166, v166
	s_nop 0
	v_add_f32_e32 v166, 1.0, v166
	v_rcp_f32_e32 v173, v166
	s_waitcnt vmcnt(4)
	v_pk_mul_f32 v[126:127], v[126:127], v[162:163]
	v_pk_mul_f32 v[128:129], v[128:129], v[164:165]
	v_pk_mul_f32 v[172:173], v[172:173], v[170:171]
	s_nop 0
	v_pk_mul_f32 v[126:127], v[172:173], v[126:127]
	s_nop 0
	v_cvt_pk_bf16_f32 v166, v126, v127
	v_lshlrev_b32_e32 v170, 16, v55
	v_and_b32_e32 v171, 0xffff0000, v55
	v_mul_f32_e32 v167, 0xbfb8aa3b, v170
	v_exp_f32_e32 v167, v167
	s_nop 0
	v_add_f32_e32 v167, 1.0, v167
	v_rcp_f32_e32 v172, v167
	v_mul_f32_e32 v167, 0xbfb8aa3b, v171
	v_exp_f32_e32 v167, v167
	s_nop 0
	v_add_f32_e32 v167, 1.0, v167
	v_rcp_f32_e32 v173, v167
	s_nop 1
	v_pk_mul_f32 v[172:173], v[172:173], v[170:171]
	s_nop 0
	v_pk_mul_f32 v[128:129], v[172:173], v[128:129]
	s_nop 0
	v_cvt_pk_bf16_f32 v167, v128, v129
	s_nop 0
	global_store_dwordx2 v[132:133], v[166:167], off offset:2400
	global_load_dwordx4 v[126:129], v[130:131], off offset:896
	s_waitcnt lgkmcnt(0)
	ds_read_b128 v[206:209], v103 offset:42240
	ds_read_b128 v[210:213], v103 offset:42304
	ds_read_b128 v[214:217], v103 offset:42368
	ds_read_b128 v[218:221], v103 offset:42432
	ds_read_b128 v[222:225], v103 offset:42496
	ds_read_b128 v[226:229], v103 offset:42560
	ds_read_b128 v[230:233], v103 offset:42624
	ds_read_b128 v[234:237], v103 offset:42688
	v_mfma_f32_16x16x32_bf16 v[162:165], v[174:177], v[0:3], 0
	v_mfma_f32_16x16x32_bf16 v[162:165], v[178:181], v[4:7], v[162:165]
	v_mfma_f32_16x16x32_bf16 v[162:165], v[182:185], v[8:11], v[162:165]
	v_mfma_f32_16x16x32_bf16 v[162:165], v[186:189], v[12:15], v[162:165]
	v_mfma_f32_16x16x32_bf16 v[162:165], v[190:193], v[16:19], v[162:165]
	v_mfma_f32_16x16x32_bf16 v[162:165], v[194:197], v[20:23], v[162:165]
	v_mfma_f32_16x16x32_bf16 v[162:165], v[198:201], v[24:27], v[162:165]
	v_mfma_f32_16x16x32_bf16 v[162:165], v[202:205], v[28:31], v[162:165]
	s_waitcnt vmcnt(30)
	v_lshlrev_b32_e32 v170, 16, v56
	v_and_b32_e32 v171, 0xffff0000, v56
	v_mul_f32_e32 v166, 0xbfb8aa3b, v170
	v_exp_f32_e32 v166, v166
	s_nop 0
	v_add_f32_e32 v166, 1.0, v166
	v_rcp_f32_e32 v172, v166
	v_mul_f32_e32 v166, 0xbfb8aa3b, v171
	v_exp_f32_e32 v166, v166
	s_nop 0
	v_add_f32_e32 v166, 1.0, v166
	v_rcp_f32_e32 v173, v166
	s_waitcnt vmcnt(4)
	v_pk_mul_f32 v[118:119], v[118:119], v[162:163]
	v_pk_mul_f32 v[120:121], v[120:121], v[164:165]
	v_pk_mul_f32 v[172:173], v[172:173], v[170:171]
	s_nop 0
	v_pk_mul_f32 v[118:119], v[172:173], v[118:119]
	s_nop 0
	v_cvt_pk_bf16_f32 v166, v118, v119
	v_lshlrev_b32_e32 v170, 16, v57
	v_and_b32_e32 v171, 0xffff0000, v57
	v_mul_f32_e32 v167, 0xbfb8aa3b, v170
	v_exp_f32_e32 v167, v167
	s_nop 0
	v_add_f32_e32 v167, 1.0, v167
	v_rcp_f32_e32 v172, v167
	v_mul_f32_e32 v167, 0xbfb8aa3b, v171
	v_exp_f32_e32 v167, v167
	s_nop 0
	v_add_f32_e32 v167, 1.0, v167
	v_rcp_f32_e32 v173, v167
	s_nop 1
	v_pk_mul_f32 v[172:173], v[172:173], v[170:171]
	s_nop 0
	v_pk_mul_f32 v[120:121], v[172:173], v[120:121]
	s_nop 0
	v_cvt_pk_bf16_f32 v167, v120, v121
	s_nop 0
	global_store_dwordx2 v[132:133], v[166:167], off offset:2432
	global_load_dwordx4 v[118:121], v[130:131], off offset:960
	s_waitcnt lgkmcnt(0)
	ds_read_b128 v[174:177], v103 offset:50688
	ds_read_b128 v[178:181], v103 offset:50752
	ds_read_b128 v[182:185], v103 offset:50816
	ds_read_b128 v[186:189], v103 offset:50880
	ds_read_b128 v[190:193], v103 offset:50944
	ds_read_b128 v[194:197], v103 offset:51008
	ds_read_b128 v[198:201], v103 offset:51072
	ds_read_b128 v[202:205], v103 offset:51136
	v_mfma_f32_16x16x32_bf16 v[162:165], v[206:209], v[0:3], 0
	v_mfma_f32_16x16x32_bf16 v[162:165], v[210:213], v[4:7], v[162:165]
	v_mfma_f32_16x16x32_bf16 v[162:165], v[214:217], v[8:11], v[162:165]
	v_mfma_f32_16x16x32_bf16 v[162:165], v[218:221], v[12:15], v[162:165]
	v_mfma_f32_16x16x32_bf16 v[162:165], v[222:225], v[16:19], v[162:165]
	v_mfma_f32_16x16x32_bf16 v[162:165], v[226:229], v[20:23], v[162:165]
	v_mfma_f32_16x16x32_bf16 v[162:165], v[230:233], v[24:27], v[162:165]
	v_mfma_f32_16x16x32_bf16 v[162:165], v[234:237], v[28:31], v[162:165]
	s_waitcnt vmcnt(31)
	v_lshlrev_b32_e32 v170, 16, v58
	v_and_b32_e32 v171, 0xffff0000, v58
	v_mul_f32_e32 v166, 0xbfb8aa3b, v170
	v_exp_f32_e32 v166, v166
	s_nop 0
	v_add_f32_e32 v166, 1.0, v166
	v_rcp_f32_e32 v172, v166
	v_mul_f32_e32 v166, 0xbfb8aa3b, v171
	v_exp_f32_e32 v166, v166
	s_nop 0
	v_add_f32_e32 v166, 1.0, v166
	v_rcp_f32_e32 v173, v166
	s_waitcnt vmcnt(4)
	v_pk_mul_f32 v[122:123], v[122:123], v[162:163]
	v_pk_mul_f32 v[124:125], v[124:125], v[164:165]
	v_pk_mul_f32 v[172:173], v[172:173], v[170:171]
	s_nop 0
	v_pk_mul_f32 v[122:123], v[172:173], v[122:123]
	s_nop 0
	v_cvt_pk_bf16_f32 v166, v122, v123
	v_lshlrev_b32_e32 v170, 16, v59
	v_and_b32_e32 v171, 0xffff0000, v59
	v_mul_f32_e32 v167, 0xbfb8aa3b, v170
	v_exp_f32_e32 v167, v167
	s_nop 0
	v_add_f32_e32 v167, 1.0, v167
	v_rcp_f32_e32 v172, v167
	v_mul_f32_e32 v167, 0xbfb8aa3b, v171
	v_exp_f32_e32 v167, v167
	s_nop 0
	v_add_f32_e32 v167, 1.0, v167
	v_rcp_f32_e32 v173, v167
	s_nop 1
	v_pk_mul_f32 v[172:173], v[172:173], v[170:171]
	s_nop 0
	v_pk_mul_f32 v[124:125], v[172:173], v[124:125]
	s_nop 0
	v_cvt_pk_bf16_f32 v167, v124, v125
	s_nop 0
	global_store_dwordx2 v[132:133], v[166:167], off offset:2464
	s_waitcnt lgkmcnt(0)
	ds_read_b128 v[206:209], v103 offset:59136
	ds_read_b128 v[210:213], v103 offset:59200
	ds_read_b128 v[214:217], v103 offset:59264
	ds_read_b128 v[218:221], v103 offset:59328
	ds_read_b128 v[222:225], v103 offset:59392
	ds_read_b128 v[226:229], v103 offset:59456
	ds_read_b128 v[230:233], v103 offset:59520
	ds_read_b128 v[234:237], v103 offset:59584
	v_mfma_f32_16x16x32_bf16 v[162:165], v[174:177], v[0:3], 0
	v_mfma_f32_16x16x32_bf16 v[162:165], v[178:181], v[4:7], v[162:165]
	v_mfma_f32_16x16x32_bf16 v[162:165], v[182:185], v[8:11], v[162:165]
	v_mfma_f32_16x16x32_bf16 v[162:165], v[186:189], v[12:15], v[162:165]
	v_mfma_f32_16x16x32_bf16 v[162:165], v[190:193], v[16:19], v[162:165]
	v_mfma_f32_16x16x32_bf16 v[162:165], v[194:197], v[20:23], v[162:165]
	v_mfma_f32_16x16x32_bf16 v[162:165], v[198:201], v[24:27], v[162:165]
	v_mfma_f32_16x16x32_bf16 v[162:165], v[202:205], v[28:31], v[162:165]
	s_waitcnt vmcnt(31)
	v_lshlrev_b32_e32 v170, 16, v60
	v_and_b32_e32 v171, 0xffff0000, v60
	v_mul_f32_e32 v166, 0xbfb8aa3b, v170
	v_exp_f32_e32 v166, v166
	s_nop 0
	v_add_f32_e32 v166, 1.0, v166
	v_rcp_f32_e32 v172, v166
	v_mul_f32_e32 v166, 0xbfb8aa3b, v171
	v_exp_f32_e32 v166, v166
	s_nop 0
	v_add_f32_e32 v166, 1.0, v166
	v_rcp_f32_e32 v173, v166
	s_waitcnt vmcnt(3)
	v_pk_mul_f32 v[126:127], v[126:127], v[162:163]
	v_pk_mul_f32 v[128:129], v[128:129], v[164:165]
	v_pk_mul_f32 v[172:173], v[172:173], v[170:171]
	s_nop 0
	v_pk_mul_f32 v[126:127], v[172:173], v[126:127]
	s_nop 0
	v_cvt_pk_bf16_f32 v166, v126, v127
	v_lshlrev_b32_e32 v170, 16, v61
	v_and_b32_e32 v171, 0xffff0000, v61
	v_mul_f32_e32 v167, 0xbfb8aa3b, v170
	v_exp_f32_e32 v167, v167
	s_nop 0
	v_add_f32_e32 v167, 1.0, v167
	v_rcp_f32_e32 v172, v167
	v_mul_f32_e32 v167, 0xbfb8aa3b, v171
	v_exp_f32_e32 v167, v167
	s_nop 0
	v_add_f32_e32 v167, 1.0, v167
	v_rcp_f32_e32 v173, v167
	s_nop 1
	v_pk_mul_f32 v[172:173], v[172:173], v[170:171]
	s_nop 0
	v_pk_mul_f32 v[128:129], v[172:173], v[128:129]
	s_nop 0
	v_cvt_pk_bf16_f32 v167, v128, v129
	s_nop 0
	global_store_dwordx2 v[132:133], v[166:167], off offset:2496
	s_waitcnt lgkmcnt(0)
	v_mfma_f32_16x16x32_bf16 v[162:165], v[206:209], v[0:3], 0
	v_mfma_f32_16x16x32_bf16 v[162:165], v[210:213], v[4:7], v[162:165]
	v_mfma_f32_16x16x32_bf16 v[162:165], v[214:217], v[8:11], v[162:165]
	v_mfma_f32_16x16x32_bf16 v[162:165], v[218:221], v[12:15], v[162:165]
	v_mfma_f32_16x16x32_bf16 v[162:165], v[222:225], v[16:19], v[162:165]
	v_mfma_f32_16x16x32_bf16 v[162:165], v[226:229], v[20:23], v[162:165]
	v_mfma_f32_16x16x32_bf16 v[162:165], v[230:233], v[24:27], v[162:165]
	v_mfma_f32_16x16x32_bf16 v[162:165], v[234:237], v[28:31], v[162:165]
	s_waitcnt vmcnt(31)
	v_lshlrev_b32_e32 v170, 16, v62
	v_and_b32_e32 v171, 0xffff0000, v62
	v_mul_f32_e32 v166, 0xbfb8aa3b, v170
	v_exp_f32_e32 v166, v166
	s_nop 0
	v_add_f32_e32 v166, 1.0, v166
	v_rcp_f32_e32 v172, v166
	v_mul_f32_e32 v166, 0xbfb8aa3b, v171
	v_exp_f32_e32 v166, v166
	s_nop 0
	v_add_f32_e32 v166, 1.0, v166
	v_rcp_f32_e32 v173, v166
	s_waitcnt vmcnt(2)
	v_pk_mul_f32 v[118:119], v[118:119], v[162:163]
	v_pk_mul_f32 v[120:121], v[120:121], v[164:165]
	v_pk_mul_f32 v[172:173], v[172:173], v[170:171]
	s_nop 0
	v_pk_mul_f32 v[118:119], v[172:173], v[118:119]
	s_nop 0
	v_cvt_pk_bf16_f32 v166, v118, v119
	v_lshlrev_b32_e32 v170, 16, v63
	v_and_b32_e32 v171, 0xffff0000, v63
	v_mul_f32_e32 v167, 0xbfb8aa3b, v170
	v_exp_f32_e32 v167, v167
	s_nop 0
	v_add_f32_e32 v167, 1.0, v167
	v_rcp_f32_e32 v172, v167
	v_mul_f32_e32 v167, 0xbfb8aa3b, v171
	v_exp_f32_e32 v167, v167
	s_nop 0
	v_add_f32_e32 v167, 1.0, v167
	v_rcp_f32_e32 v173, v167
	s_nop 1
	v_pk_mul_f32 v[172:173], v[172:173], v[170:171]
	s_nop 0
	v_pk_mul_f32 v[120:121], v[172:173], v[120:121]
	s_nop 0
	v_cvt_pk_bf16_f32 v167, v120, v121
	s_nop 0
	global_store_dwordx2 v[132:133], v[166:167], off offset:2528
	s_cmp_lg_u32 s0, 0
	s_cbranch_scc1 .LBB0_554
	v_mov_b32_e32 v252, 0x3000
	s_mov_b32 s13, 0
